# attention QK: K-fragment ds_reads reordered (fa first) so MFMAs start at lgkmcnt(8)
# speedup vs baseline: 1.0053x; 1.0053x over previous
.LBB0_1702:
	s_add_i32 s20, s47, s43
	v_lshl_add_u64 v[66:67], s[44:45], 0, v[174:175]
	s_mov_b32 m0, s20
	s_add_i32 s43, s61, 0xfffffbf1
	global_load_lds_dwordx4 v[66:67], off
	v_lshl_add_u64 v[66:67], s[44:45], 0, v[178:179]
	s_add_i32 m0, s20, 0x400
	s_add_i32 s20, s62, 0
	global_load_lds_dwordx4 v[66:67], off
	s_cmpk_lt_i32 s43, 0x80
	s_cselect_b64 s[44:45], -1, 0
	s_cmp_gt_i32 s61, 0x3fffffff
	s_cselect_b64 s[64:65], -1, 0
	s_or_b64 s[64:65], s[44:45], s[64:65]
	v_add_u32_e32 v66, s20, v137
	s_mov_b64 s[44:45], -1
	s_and_b64 vcc, exec, s[64:65]
	v_add_u32_e32 v157, v66, v138
	v_add_u32_e32 v156, v66, v140
	v_add_u32_e32 v154, v66, v141
	v_add_u32_e32 v153, v66, v142
	s_cbranch_vccnz .LBB0_1704
	v_mov_b32_e32 v66, s52
	ds_read_b32 v66, v66 offset:512
	s_waitcnt lgkmcnt(0)
	v_sub_f32_e32 v162, v66, v195
	ds_read_b128 v[66:69], v157 offset:32768
	ds_read_b128 v[82:85], v157 offset:40960
	ds_read_b128 v[204:207], v156 offset:32768
	ds_read_b128 v[212:215], v156 offset:40960
	ds_read_b128 v[220:223], v154 offset:32768
	ds_read_b128 v[228:231], v154 offset:40960
	ds_read_b128 v[236:239], v153 offset:32768
	ds_read_b128 v[244:247], v153 offset:40960
	ds_read_b128 v[196:199], v157 offset:32896
	ds_read_b128 v[200:203], v157 offset:41088
	ds_read_b128 v[208:211], v156 offset:32896
	ds_read_b128 v[216:219], v156 offset:41088
	ds_read_b128 v[224:227], v154 offset:32896
	ds_read_b128 v[232:235], v154 offset:41088
	ds_read_b128 v[240:243], v153 offset:32896
	ds_read_b128 v[248:251], v153 offset:41088
	s_waitcnt lgkmcnt(8)
	v_mfma_f32_32x32x16_bf16 v[66:81], v[66:69], v[98:101], 0
	v_mfma_f32_32x32x16_bf16 v[82:97], v[82:85], v[98:101], 0
	v_mfma_f32_32x32x16_bf16 v[66:81], v[204:207], v[102:105], v[66:81]
	v_mfma_f32_32x32x16_bf16 v[82:97], v[212:215], v[102:105], v[82:97]
	v_mfma_f32_32x32x16_bf16 v[66:81], v[220:223], v[106:109], v[66:81]
	v_mfma_f32_32x32x16_bf16 v[82:97], v[228:231], v[106:109], v[82:97]
	v_mfma_f32_32x32x16_bf16 v[66:81], v[236:239], v[110:113], v[66:81]
	v_mfma_f32_32x32x16_bf16 v[82:97], v[244:247], v[110:113], v[82:97]
	s_waitcnt lgkmcnt(0)
	v_mfma_f32_32x32x16_bf16 v[66:81], v[196:199], v[114:117], v[66:81]
	v_mfma_f32_32x32x16_bf16 v[82:97], v[200:203], v[114:117], v[82:97]
	v_mfma_f32_32x32x16_bf16 v[66:81], v[208:211], v[118:121], v[66:81]
	v_mfma_f32_32x32x16_bf16 v[82:97], v[216:219], v[118:121], v[82:97]
	v_mfma_f32_32x32x16_bf16 v[66:81], v[224:227], v[122:125], v[66:81]
	v_mfma_f32_32x32x16_bf16 v[82:97], v[232:235], v[122:125], v[82:97]
	v_mfma_f32_32x32x16_bf16 v[66:81], v[240:243], v[126:129], v[66:81]
	v_mfma_f32_32x32x16_bf16 v[82:97], v[248:251], v[126:129], v[82:97]
	s_mov_b64 s[44:45], 0

.LBB0_1987:
	s_or_b64 exec, exec, s[44:45]
	v_add_u32_e32 v66, s62, v137
	v_add_u32_e32 v74, v66, v138
	v_add_u32_e32 v75, v66, v140
	v_add_u32_e32 v76, v66, v141
	v_add_u32_e32 v77, v66, v142
	ds_read_b128 v[66:69], v74 offset:32768
	ds_read_b128 v[70:73], v74 offset:40960
	ds_read_b128 v[194:197], v75 offset:32768
	ds_read_b128 v[202:205], v75 offset:40960
	ds_read_b128 v[210:213], v76 offset:32768
	ds_read_b128 v[218:221], v76 offset:40960
	ds_read_b128 v[226:229], v77 offset:32768
	ds_read_b128 v[234:237], v77 offset:40960
	ds_read_b128 v[158:161], v74 offset:32896
	ds_read_b128 v[164:167], v74 offset:41088
	ds_read_b128 v[198:201], v75 offset:32896
	ds_read_b128 v[206:209], v75 offset:41088
	ds_read_b128 v[214:217], v76 offset:32896
	ds_read_b128 v[222:225], v76 offset:41088
	ds_read_b128 v[230:233], v77 offset:32896
	ds_read_b128 v[238:241], v77 offset:41088
	s_waitcnt lgkmcnt(8)
	v_mfma_f32_32x32x16_bf16 v[82:97], v[66:69], v[98:101], 0
	v_mfma_f32_32x32x16_bf16 v[66:81], v[70:73], v[98:101], 0
	v_mfma_f32_32x32x16_bf16 v[82:97], v[194:197], v[102:105], v[82:97]
	v_mfma_f32_32x32x16_bf16 v[66:81], v[202:205], v[102:105], v[66:81]
	v_mfma_f32_32x32x16_bf16 v[82:97], v[210:213], v[106:109], v[82:97]
	v_mfma_f32_32x32x16_bf16 v[66:81], v[218:221], v[106:109], v[66:81]
	v_mfma_f32_32x32x16_bf16 v[82:97], v[226:229], v[110:113], v[82:97]
	v_mfma_f32_32x32x16_bf16 v[66:81], v[234:237], v[110:113], v[66:81]
	s_waitcnt lgkmcnt(0)
	v_mfma_f32_32x32x16_bf16 v[82:97], v[158:161], v[114:117], v[82:97]
	v_mfma_f32_32x32x16_bf16 v[66:81], v[164:167], v[114:117], v[66:81]
	v_mfma_f32_32x32x16_bf16 v[82:97], v[198:201], v[118:121], v[82:97]
	v_mfma_f32_32x32x16_bf16 v[66:81], v[206:209], v[118:121], v[66:81]
	v_mfma_f32_32x32x16_bf16 v[82:97], v[214:217], v[122:125], v[82:97]
	v_mfma_f32_32x32x16_bf16 v[66:81], v[222:225], v[122:125], v[66:81]
	v_mfma_f32_32x32x16_bf16 v[82:97], v[230:233], v[126:129], v[82:97]
	v_mfma_f32_32x32x16_bf16 v[66:81], v[238:241], v[126:129], v[66:81]
.LBB0_1988:
	s_andn2_saveexec_b64 s[10:11], s[12:13]
	s_cbranch_execz .LBB0_1974
	s_nop 9
	v_add_u32_e32 v66, s62, v137
	v_cndmask_b32_e64 v0, -v153, v186, vcc
	v_add_u32_e32 v162, v66, v138
	v_add_u32_e32 v161, v66, v140
	v_add_u32_e32 v160, v66, v141
	v_add_u32_e32 v158, v66, v142
	s_and_saveexec_b64 s[12:13], s[8:9]
	s_xor_b64 s[8:9], exec, s[12:13]
	s_cbranch_execz .LBB0_1991
	v_sub_u32_e32 v0, v180, v150
	v_lshl_add_u32 v0, v0, 2, v152
	v_add_u32_e32 v66, 0x400, v0
	v_add_u32_e32 v68, 0x408, v0
	v_add_u32_e32 v70, 0x420, v0
	v_add_u32_e32 v72, 0x428, v0
	v_add_u32_e32 v74, 0x440, v0
	v_add_u32_e32 v76, 0x448, v0
	v_add_u32_e32 v78, 0x460, v0
	v_add_u32_e32 v80, 0x468, v0
	ds_read2_b32 v[82:83], v0 offset0:224 offset1:225
	ds_read2_b32 v[84:85], v0 offset0:226 offset1:227
	ds_read2_b32 v[86:87], v0 offset0:232 offset1:233
	ds_read2_b32 v[88:89], v0 offset0:234 offset1:235
	ds_read2_b32 v[66:67], v66 offset1:1
	ds_read2_b32 v[68:69], v68 offset1:1
	ds_read2_b32 v[70:71], v70 offset1:1
	ds_read2_b32 v[72:73], v72 offset1:1
	ds_read2_b32 v[90:91], v0 offset0:240 offset1:241
	ds_read2_b32 v[92:93], v0 offset0:242 offset1:243
	ds_read2_b32 v[94:95], v0 offset0:248 offset1:249
	ds_read2_b32 v[96:97], v0 offset0:250 offset1:251
	ds_read2_b32 v[74:75], v74 offset1:1
	ds_read2_b32 v[76:77], v76 offset1:1
	ds_read2_b32 v[78:79], v78 offset1:1
	ds_read2_b32 v[80:81], v80 offset1:1
	v_cndmask_b32_e64 v0, -v153, v186, vcc
	ds_read_b128 v[164:167], v162 offset:32768
	ds_read_b128 v[198:201], v162 offset:40960
	ds_read_b128 v[206:209], v161 offset:32768
	ds_read_b128 v[214:217], v161 offset:40960
	ds_read_b128 v[222:225], v160 offset:32768
	ds_read_b128 v[230:233], v160 offset:40960
	ds_read_b128 v[238:241], v158 offset:32768
	ds_read_b128 v[246:249], v158 offset:40960
	ds_read_b128 v[194:197], v162 offset:32896
	ds_read_b128 v[202:205], v162 offset:41088
	ds_read_b128 v[210:213], v161 offset:32896
	ds_read_b128 v[218:221], v161 offset:41088
	ds_read_b128 v[226:229], v160 offset:32896
	ds_read_b128 v[234:237], v160 offset:41088
	ds_read_b128 v[242:245], v158 offset:32896
	ds_read_b128 v[158:161], v158 offset:41088
	s_waitcnt lgkmcnt(8)
	v_mfma_f32_32x32x16_bf16 v[82:97], v[164:167], v[98:101], v[82:97]
	v_mfma_f32_32x32x16_bf16 v[66:81], v[198:201], v[98:101], v[66:81]
	v_mfma_f32_32x32x16_bf16 v[82:97], v[206:209], v[102:105], v[82:97]
	v_mfma_f32_32x32x16_bf16 v[66:81], v[214:217], v[102:105], v[66:81]
	v_mfma_f32_32x32x16_bf16 v[82:97], v[222:225], v[106:109], v[82:97]
	v_mfma_f32_32x32x16_bf16 v[66:81], v[230:233], v[106:109], v[66:81]
	v_mfma_f32_32x32x16_bf16 v[82:97], v[238:241], v[110:113], v[82:97]
	v_mfma_f32_32x32x16_bf16 v[66:81], v[246:249], v[110:113], v[66:81]
	s_waitcnt lgkmcnt(0)
	v_mfma_f32_32x32x16_bf16 v[82:97], v[194:197], v[114:117], v[82:97]
	v_mfma_f32_32x32x16_bf16 v[66:81], v[202:205], v[114:117], v[66:81]
	v_mfma_f32_32x32x16_bf16 v[82:97], v[210:213], v[118:121], v[82:97]
	v_mfma_f32_32x32x16_bf16 v[66:81], v[218:221], v[118:121], v[66:81]
	v_mfma_f32_32x32x16_bf16 v[82:97], v[226:229], v[122:125], v[82:97]
	v_mfma_f32_32x32x16_bf16 v[66:81], v[234:237], v[122:125], v[66:81]
	v_mfma_f32_32x32x16_bf16 v[82:97], v[242:245], v[126:129], v[82:97]
	v_mfma_f32_32x32x16_bf16 v[66:81], v[158:161], v[126:129], v[66:81]
.LBB0_1991:
	s_andn2_saveexec_b64 s[8:9], s[8:9]
	s_cbranch_execz .LBB0_1973
	s_nop 9
	v_or_b32_e32 v66, v180, v144
	v_sub_u32_e32 v66, v150, v66
	v_subrev_u32_e32 v67, 32, v66
	v_add_u32_e32 v70, -1, v66
	v_subrev_u32_e32 v71, 33, v66
	v_add_u32_e32 v74, -2, v66
	v_subrev_u32_e32 v75, 34, v66
	v_add_u32_e32 v78, -3, v66
	v_subrev_u32_e32 v79, 35, v66
	v_add_u32_e32 v86, -8, v66
	v_add_u32_e32 v90, -10, v66
	v_subrev_u32_e32 v91, 42, v66
	v_add_u32_e32 v94, -11, v66
	v_subrev_u32_e32 v95, 43, v66
	v_med3_i32 v68, v66, 0, v184
	v_med3_i32 v69, v67, 0, v184
	v_med3_i32 v72, v70, 0, v184
	v_med3_i32 v73, v71, 0, v184
	v_med3_i32 v76, v74, 0, v184
	v_med3_i32 v77, v75, 0, v184
	v_med3_i32 v80, v78, 0, v184
	v_med3_i32 v81, v79, 0, v184
	v_subrev_u32_e32 v87, 40, v66
	v_med3_i32 v82, v86, 0, v184
	v_add_u32_e32 v88, -9, v66
	v_subrev_u32_e32 v89, 41, v66
	v_med3_i32 v92, v90, 0, v184
	v_med3_i32 v93, v91, 0, v184
	v_med3_i32 v96, v94, 0, v184
	v_med3_i32 v97, v95, 0, v184
	v_lshl_add_u32 v68, v68, 2, s52
	v_lshl_add_u32 v69, v69, 2, s52
	v_lshl_add_u32 v72, v72, 2, s52
	v_lshl_add_u32 v73, v73, 2, s52
	v_lshl_add_u32 v76, v76, 2, s52
	v_lshl_add_u32 v77, v77, 2, s52
	v_lshl_add_u32 v80, v80, 2, s52
	v_lshl_add_u32 v81, v81, 2, s52
	v_lshl_add_u32 v82, v82, 2, s52
	v_med3_i32 v83, v87, 0, v184
	v_med3_i32 v84, v88, 0, v184
	v_med3_i32 v85, v89, 0, v184
	v_lshl_add_u32 v92, v92, 2, s52
	v_lshl_add_u32 v93, v93, 2, s52
	v_lshl_add_u32 v96, v96, 2, s52
	v_lshl_add_u32 v97, v97, 2, s52
	v_add_u32_e32 v167, -16, v66
	v_subrev_u32_e32 v196, 18, v66
	v_subrev_u32_e32 v197, 50, v66
	v_subrev_u32_e32 v200, 19, v66
	v_subrev_u32_e32 v201, 51, v66
	ds_read_b32 v68, v68
	ds_read_b32 v69, v69
	ds_read_b32 v72, v72
	ds_read_b32 v73, v73
	ds_read_b32 v76, v76
	ds_read_b32 v77, v77
	ds_read_b32 v80, v80
	ds_read_b32 v81, v81
	v_lshl_add_u32 v83, v83, 2, s52
	v_lshl_add_u32 v84, v84, 2, s52
	v_lshl_add_u32 v85, v85, 2, s52
	ds_read_b32 v159, v82
	ds_read_b32 v164, v83
	ds_read_b32 v165, v84
	ds_read_b32 v166, v85
	ds_read_b32 v92, v92
	ds_read_b32 v93, v93
	ds_read_b32 v96, v96
	ds_read_b32 v97, v97
	v_subrev_u32_e32 v180, 48, v66
	v_med3_i32 v82, v167, 0, v184
	v_subrev_u32_e32 v194, 17, v66
	v_subrev_u32_e32 v195, 49, v66
	v_med3_i32 v198, v196, 0, v184
	v_med3_i32 v199, v197, 0, v184
	v_med3_i32 v202, v200, 0, v184
	v_med3_i32 v203, v201, 0, v184
	v_lshl_add_u32 v82, v82, 2, s52
	v_med3_i32 v83, v180, 0, v184
	v_med3_i32 v84, v194, 0, v184
	v_med3_i32 v85, v195, 0, v184
	v_lshl_add_u32 v198, v198, 2, s52
	v_lshl_add_u32 v199, v199, 2, s52
	v_lshl_add_u32 v202, v202, 2, s52
	v_lshl_add_u32 v203, v203, 2, s52
	v_subrev_u32_e32 v208, 24, v66
	v_subrev_u32_e32 v212, 26, v66
	v_subrev_u32_e32 v213, 58, v66
	v_subrev_u32_e32 v216, 27, v66
	v_subrev_u32_e32 v217, 59, v66
	v_lshl_add_u32 v83, v83, 2, s52
	v_lshl_add_u32 v84, v84, 2, s52
	v_lshl_add_u32 v85, v85, 2, s52
	ds_read_b32 v204, v82
	ds_read_b32 v205, v83
	ds_read_b32 v206, v84
	ds_read_b32 v207, v85
	ds_read_b32 v198, v198
	ds_read_b32 v199, v199
	ds_read_b32 v202, v202
	ds_read_b32 v203, v203
	v_subrev_u32_e32 v209, 56, v66
	v_med3_i32 v82, v208, 0, v184
	v_subrev_u32_e32 v210, 25, v66
	v_subrev_u32_e32 v211, 57, v66
	v_med3_i32 v214, v212, 0, v184
	v_med3_i32 v215, v213, 0, v184
	v_med3_i32 v218, v216, 0, v184
	v_med3_i32 v219, v217, 0, v184
	v_lshl_add_u32 v82, v82, 2, s52
	v_med3_i32 v83, v209, 0, v184
	v_med3_i32 v84, v210, 0, v184
	v_med3_i32 v85, v211, 0, v184
	v_lshl_add_u32 v214, v214, 2, s52
	v_lshl_add_u32 v215, v215, 2, s52
	v_lshl_add_u32 v218, v218, 2, s52
	v_lshl_add_u32 v219, v219, 2, s52
	v_cmp_gt_u32_e32 vcc, 2.0, v66
	v_lshl_add_u32 v83, v83, 2, s52
	v_lshl_add_u32 v84, v84, 2, s52
	v_lshl_add_u32 v85, v85, 2, s52
	ds_read_b32 v220, v82
	ds_read_b32 v221, v83
	ds_read_b32 v222, v84
	ds_read_b32 v223, v85
	ds_read_b32 v214, v214
	ds_read_b32 v215, v215
	ds_read_b32 v218, v218
	ds_read_b32 v219, v219
	s_waitcnt lgkmcnt(0)
	v_cndmask_b32_e32 v82, v186, v68, vcc
	v_cmp_gt_u32_e32 vcc, 2.0, v67
	s_waitcnt lgkmcnt(0)
	s_nop 1
	v_cndmask_b32_e32 v66, v186, v69, vcc
	v_cmp_gt_u32_e32 vcc, 2.0, v70
	s_nop 1
	v_cndmask_b32_e32 v83, v186, v72, vcc
	v_cmp_gt_u32_e32 vcc, 2.0, v71
	s_nop 1
	v_cndmask_b32_e32 v67, v186, v73, vcc
	v_cmp_gt_u32_e32 vcc, 2.0, v74
	s_nop 1
	v_cndmask_b32_e32 v84, v186, v76, vcc
	v_cmp_gt_u32_e32 vcc, 2.0, v75
	s_nop 1
	v_cndmask_b32_e32 v68, v186, v77, vcc
	v_cmp_gt_u32_e32 vcc, 2.0, v78
	s_nop 1
	v_cndmask_b32_e32 v85, v186, v80, vcc
	v_cmp_gt_u32_e32 vcc, 2.0, v79
	s_nop 1
	v_cndmask_b32_e32 v69, v186, v81, vcc
	v_cmp_gt_u32_e32 vcc, 2.0, v86
	s_nop 1
	v_cndmask_b32_e32 v86, v186, v159, vcc
	v_cmp_gt_u32_e32 vcc, 2.0, v87
	s_nop 1
	v_cndmask_b32_e32 v70, v186, v164, vcc
	v_cmp_gt_u32_e32 vcc, 2.0, v88
	s_nop 1
	v_cndmask_b32_e32 v87, v186, v165, vcc
	v_cmp_gt_u32_e32 vcc, 2.0, v89
	s_nop 1
	v_cndmask_b32_e32 v71, v186, v166, vcc
	v_cmp_gt_u32_e32 vcc, 2.0, v90
	s_nop 1
	v_cndmask_b32_e32 v88, v186, v92, vcc
	v_cmp_gt_u32_e32 vcc, 2.0, v91
	s_nop 1
	v_cndmask_b32_e32 v72, v186, v93, vcc
	v_cmp_gt_u32_e32 vcc, 2.0, v94
	s_nop 1
	v_cndmask_b32_e32 v89, v186, v96, vcc
	v_cmp_gt_u32_e32 vcc, 2.0, v95
	s_nop 1
	v_cndmask_b32_e32 v73, v186, v97, vcc
	v_cmp_gt_u32_e32 vcc, 2.0, v167
	s_nop 1
	v_cndmask_b32_e32 v90, v186, v204, vcc
	v_cmp_gt_u32_e32 vcc, 2.0, v180
	s_nop 1
	v_cndmask_b32_e32 v74, v186, v205, vcc
	v_cmp_gt_u32_e32 vcc, 2.0, v194
	s_nop 1
	v_cndmask_b32_e32 v91, v186, v206, vcc
	v_cmp_gt_u32_e32 vcc, 2.0, v195
	s_nop 1
	v_cndmask_b32_e32 v75, v186, v207, vcc
	v_cmp_gt_u32_e32 vcc, 2.0, v196
	s_nop 1
	v_cndmask_b32_e32 v92, v186, v198, vcc
	v_cmp_gt_u32_e32 vcc, 2.0, v197
	s_nop 1
	v_cndmask_b32_e32 v76, v186, v199, vcc
	v_cmp_gt_u32_e32 vcc, 2.0, v200
	s_nop 1
	v_cndmask_b32_e32 v93, v186, v202, vcc
	v_cmp_gt_u32_e32 vcc, 2.0, v201
	s_nop 1
	v_cndmask_b32_e32 v77, v186, v203, vcc
	v_cmp_gt_u32_e32 vcc, 2.0, v208
	s_nop 1
	v_cndmask_b32_e32 v94, v186, v220, vcc
	v_cmp_gt_u32_e32 vcc, 2.0, v209
	s_nop 1
	v_cndmask_b32_e32 v78, v186, v221, vcc
	v_cmp_gt_u32_e32 vcc, 2.0, v210
	s_nop 1
	v_cndmask_b32_e32 v95, v186, v222, vcc
	v_cmp_gt_u32_e32 vcc, 2.0, v211
	s_nop 1
	v_cndmask_b32_e32 v79, v186, v223, vcc
	v_cmp_gt_u32_e32 vcc, 2.0, v212
	s_nop 1
	v_cndmask_b32_e32 v96, v186, v214, vcc
	v_cmp_gt_u32_e32 vcc, 2.0, v213
	s_nop 1
	v_cndmask_b32_e32 v80, v186, v215, vcc
	v_cmp_gt_u32_e32 vcc, 2.0, v216
	s_nop 1
	v_cndmask_b32_e32 v97, v186, v218, vcc
	v_cmp_gt_u32_e32 vcc, 2.0, v217
	s_nop 1
	v_cndmask_b32_e32 v81, v186, v219, vcc
	ds_read_b128 v[164:167], v162 offset:32768
	ds_read_b128 v[198:201], v162 offset:40960
	ds_read_b128 v[206:209], v161 offset:32768
	ds_read_b128 v[214:217], v161 offset:40960
	ds_read_b128 v[222:225], v160 offset:32768
	ds_read_b128 v[230:233], v160 offset:40960
	ds_read_b128 v[238:241], v158 offset:32768
	ds_read_b128 v[246:249], v158 offset:40960
	ds_read_b128 v[194:197], v162 offset:32896
	ds_read_b128 v[202:205], v162 offset:41088
	ds_read_b128 v[210:213], v161 offset:32896
	ds_read_b128 v[218:221], v161 offset:41088
	ds_read_b128 v[226:229], v160 offset:32896
	ds_read_b128 v[234:237], v160 offset:41088
	ds_read_b128 v[242:245], v158 offset:32896
	ds_read_b128 v[158:161], v158 offset:41088
	s_waitcnt lgkmcnt(8)
	v_mfma_f32_32x32x16_bf16 v[82:97], v[164:167], v[98:101], v[82:97]
	v_mfma_f32_32x32x16_bf16 v[66:81], v[198:201], v[98:101], v[66:81]
	v_mfma_f32_32x32x16_bf16 v[82:97], v[206:209], v[102:105], v[82:97]
	v_mfma_f32_32x32x16_bf16 v[66:81], v[214:217], v[102:105], v[66:81]
	v_mfma_f32_32x32x16_bf16 v[82:97], v[222:225], v[106:109], v[82:97]
	v_mfma_f32_32x32x16_bf16 v[66:81], v[230:233], v[106:109], v[66:81]
	v_mfma_f32_32x32x16_bf16 v[82:97], v[238:241], v[110:113], v[82:97]
	v_mfma_f32_32x32x16_bf16 v[66:81], v[246:249], v[110:113], v[66:81]
	s_waitcnt lgkmcnt(0)
	v_mfma_f32_32x32x16_bf16 v[82:97], v[194:197], v[114:117], v[82:97]
	v_mfma_f32_32x32x16_bf16 v[66:81], v[202:205], v[114:117], v[66:81]
	v_mfma_f32_32x32x16_bf16 v[82:97], v[210:213], v[118:121], v[82:97]
	v_mfma_f32_32x32x16_bf16 v[66:81], v[218:221], v[118:121], v[66:81]
	v_mfma_f32_32x32x16_bf16 v[82:97], v[226:229], v[122:125], v[82:97]
	v_mfma_f32_32x32x16_bf16 v[66:81], v[234:237], v[122:125], v[66:81]
	v_mfma_f32_32x32x16_bf16 v[82:97], v[242:245], v[126:129], v[82:97]
	v_mfma_f32_32x32x16_bf16 v[66:81], v[158:161], v[126:129], v[66:81]
	s_branch .LBB0_1973

.LBB0_2001:
	s_lshl_b32 s13, s61, 6
	s_sub_i32 s8, s54, s13
	s_sub_i32 s14, s60, s13
	s_cmpk_lt_i32 s8, 0x80
	s_cselect_b64 s[10:11], -1, 0
	s_cmpk_lt_i32 s14, 0x201
	s_cselect_b64 s[8:9], -1, 0
	s_cmpk_gt_i32 s14, 0x200
	v_add_u32_e32 v66, 0, v133
	s_cselect_b64 s[14:15], -1, 0
	s_or_b64 s[14:15], s[10:11], s[14:15]
	v_add_u32_e32 v66, v66, v137
	s_mov_b64 s[10:11], -1
	s_and_b64 vcc, exec, s[14:15]
	v_add_u32_e32 v153, v66, v138
	v_add_u32_e32 v145, v66, v140
	v_add_u32_e32 v135, v66, v141
	v_add_u32_e32 v134, v66, v142
	s_cbranch_vccnz .LBB0_2003
	v_mov_b32_e32 v66, s52
	ds_read_b32 v66, v66 offset:512
	s_waitcnt lgkmcnt(0)
	v_sub_f32_e32 v154, v66, v131
	ds_read_b128 v[66:69], v153 offset:32768
	ds_read_b128 v[70:73], v153 offset:40960
	ds_read_b128 v[190:193], v145 offset:32768
	ds_read_b128 v[198:201], v145 offset:40960
	ds_read_b128 v[206:209], v135 offset:32768
	ds_read_b128 v[214:217], v135 offset:40960
	ds_read_b128 v[222:225], v134 offset:32768
	ds_read_b128 v[230:233], v134 offset:40960
	ds_read_b128 v[156:159], v153 offset:32896
	ds_read_b128 v[164:167], v153 offset:41088
	ds_read_b128 v[194:197], v145 offset:32896
	ds_read_b128 v[202:205], v145 offset:41088
	ds_read_b128 v[210:213], v135 offset:32896
	ds_read_b128 v[218:221], v135 offset:41088
	ds_read_b128 v[226:229], v134 offset:32896
	ds_read_b128 v[234:237], v134 offset:41088
	s_waitcnt lgkmcnt(8)
	v_mfma_f32_32x32x16_bf16 v[82:97], v[66:69], v[98:101], 0
	v_mfma_f32_32x32x16_bf16 v[66:81], v[70:73], v[98:101], 0
	v_mfma_f32_32x32x16_bf16 v[82:97], v[190:193], v[102:105], v[82:97]
	v_mfma_f32_32x32x16_bf16 v[66:81], v[198:201], v[102:105], v[66:81]
	v_mfma_f32_32x32x16_bf16 v[82:97], v[206:209], v[106:109], v[82:97]
	v_mfma_f32_32x32x16_bf16 v[66:81], v[214:217], v[106:109], v[66:81]
	v_mfma_f32_32x32x16_bf16 v[82:97], v[222:225], v[110:113], v[82:97]
	v_mfma_f32_32x32x16_bf16 v[66:81], v[230:233], v[110:113], v[66:81]
	s_waitcnt lgkmcnt(0)
	v_mfma_f32_32x32x16_bf16 v[82:97], v[156:159], v[114:117], v[82:97]
	v_mfma_f32_32x32x16_bf16 v[66:81], v[164:167], v[114:117], v[66:81]
	v_mfma_f32_32x32x16_bf16 v[82:97], v[194:197], v[118:121], v[82:97]
	v_mfma_f32_32x32x16_bf16 v[66:81], v[202:205], v[118:121], v[66:81]
	v_mfma_f32_32x32x16_bf16 v[82:97], v[210:213], v[122:125], v[82:97]
	v_mfma_f32_32x32x16_bf16 v[66:81], v[218:221], v[122:125], v[66:81]
	v_mfma_f32_32x32x16_bf16 v[82:97], v[226:229], v[126:129], v[82:97]
	v_mfma_f32_32x32x16_bf16 v[66:81], v[234:237], v[126:129], v[66:81]
	s_mov_b64 s[10:11], 0
.LBB0_2003:
	s_andn2_b64 vcc, exec, s[10:11]
	s_cbranch_vccnz .LBB0_2009
	s_andn2_b64 vcc, exec, s[8:9]
	s_mov_b64 s[8:9], -1
	s_cbranch_vccnz .LBB0_2006
	s_nop 5
	v_sub_u32_e32 v66, s13, v150
	v_lshl_add_u32 v74, v66, 2, v152
	v_add_u32_e32 v66, 0x400, v74
	v_add_u32_e32 v68, 0x408, v74
	v_add_u32_e32 v70, 0x420, v74
	v_add_u32_e32 v72, 0x428, v74
	v_add_u32_e32 v75, 0x440, v74
	v_add_u32_e32 v76, 0x448, v74
	v_add_u32_e32 v78, 0x460, v74
	v_add_u32_e32 v80, 0x468, v74
	ds_read2_b32 v[82:83], v74 offset0:224 offset1:225
	ds_read2_b32 v[84:85], v74 offset0:226 offset1:227
	ds_read2_b32 v[86:87], v74 offset0:232 offset1:233
	ds_read2_b32 v[88:89], v74 offset0:234 offset1:235
	ds_read2_b32 v[66:67], v66 offset1:1
	ds_read2_b32 v[68:69], v68 offset1:1
	ds_read2_b32 v[70:71], v70 offset1:1
	ds_read2_b32 v[72:73], v72 offset1:1
	ds_read2_b32 v[90:91], v74 offset0:240 offset1:241
	ds_read2_b32 v[92:93], v74 offset0:242 offset1:243
	ds_read2_b32 v[94:95], v74 offset0:248 offset1:249
	ds_read2_b32 v[96:97], v74 offset0:250 offset1:251
	ds_read2_b32 v[74:75], v75 offset1:1
	ds_read2_b32 v[76:77], v76 offset1:1
	ds_read2_b32 v[78:79], v78 offset1:1
	ds_read2_b32 v[80:81], v80 offset1:1
	ds_read_b128 v[156:159], v153 offset:32768
	ds_read_b128 v[190:193], v153 offset:40960
	ds_read_b128 v[198:201], v145 offset:32768
	ds_read_b128 v[206:209], v145 offset:40960
	ds_read_b128 v[214:217], v135 offset:32768
	ds_read_b128 v[222:225], v135 offset:40960
	ds_read_b128 v[230:233], v134 offset:32768
	ds_read_b128 v[238:241], v134 offset:40960
	ds_read_b128 v[164:167], v153 offset:32896
	ds_read_b128 v[194:197], v153 offset:41088
	ds_read_b128 v[202:205], v145 offset:32896
	ds_read_b128 v[210:213], v145 offset:41088
	ds_read_b128 v[218:221], v135 offset:32896
	ds_read_b128 v[226:229], v135 offset:41088
	ds_read_b128 v[234:237], v134 offset:32896
	ds_read_b128 v[242:245], v134 offset:41088
	s_waitcnt lgkmcnt(8)
	v_mfma_f32_32x32x16_bf16 v[82:97], v[156:159], v[98:101], v[82:97]
	v_mfma_f32_32x32x16_bf16 v[66:81], v[190:193], v[98:101], v[66:81]
	v_mfma_f32_32x32x16_bf16 v[82:97], v[198:201], v[102:105], v[82:97]
	v_mfma_f32_32x32x16_bf16 v[66:81], v[206:209], v[102:105], v[66:81]
	v_mfma_f32_32x32x16_bf16 v[82:97], v[214:217], v[106:109], v[82:97]
	v_mfma_f32_32x32x16_bf16 v[66:81], v[222:225], v[106:109], v[66:81]
	v_mfma_f32_32x32x16_bf16 v[82:97], v[230:233], v[110:113], v[82:97]
	v_mfma_f32_32x32x16_bf16 v[66:81], v[238:241], v[110:113], v[66:81]
	s_waitcnt lgkmcnt(0)
	v_mfma_f32_32x32x16_bf16 v[82:97], v[164:167], v[114:117], v[82:97]
	v_mfma_f32_32x32x16_bf16 v[66:81], v[194:197], v[114:117], v[66:81]
	v_mfma_f32_32x32x16_bf16 v[82:97], v[202:205], v[118:121], v[82:97]
	v_mfma_f32_32x32x16_bf16 v[66:81], v[210:213], v[118:121], v[66:81]
	v_mfma_f32_32x32x16_bf16 v[82:97], v[218:221], v[122:125], v[82:97]
	v_mfma_f32_32x32x16_bf16 v[66:81], v[226:229], v[122:125], v[66:81]
	v_mfma_f32_32x32x16_bf16 v[82:97], v[234:237], v[126:129], v[82:97]
	v_mfma_f32_32x32x16_bf16 v[66:81], v[242:245], v[126:129], v[66:81]
	s_mov_b64 s[8:9], 0
.LBB0_2006:
	s_andn2_b64 vcc, exec, s[8:9]
	s_cbranch_vccnz .LBB0_2008
	s_nop 8
	v_or_b32_e32 v66, s13, v144
	v_sub_u32_e32 v66, v150, v66
	v_subrev_u32_e32 v67, 32, v66
	v_add_u32_e32 v70, -1, v66
	v_subrev_u32_e32 v71, 33, v66
	v_add_u32_e32 v74, -2, v66
	v_subrev_u32_e32 v75, 34, v66
	v_add_u32_e32 v78, -3, v66
	v_subrev_u32_e32 v79, 35, v66
	v_add_u32_e32 v86, -8, v66
	v_add_u32_e32 v90, -10, v66
	v_subrev_u32_e32 v91, 42, v66
	v_add_u32_e32 v94, -11, v66
	v_subrev_u32_e32 v95, 43, v66
	v_med3_i32 v68, v66, 0, v184
	v_med3_i32 v69, v67, 0, v184
	v_med3_i32 v72, v70, 0, v184
	v_med3_i32 v73, v71, 0, v184
	v_med3_i32 v76, v74, 0, v184
	v_med3_i32 v77, v75, 0, v184
	v_med3_i32 v80, v78, 0, v184
	v_med3_i32 v81, v79, 0, v184
	v_subrev_u32_e32 v87, 40, v66
	v_med3_i32 v82, v86, 0, v184
	v_add_u32_e32 v88, -9, v66
	v_subrev_u32_e32 v89, 41, v66
	v_med3_i32 v92, v90, 0, v184
	v_med3_i32 v93, v91, 0, v184
	v_med3_i32 v96, v94, 0, v184
	v_med3_i32 v97, v95, 0, v184
	v_lshl_add_u32 v68, v68, 2, s52
	v_lshl_add_u32 v69, v69, 2, s52
	v_lshl_add_u32 v72, v72, 2, s52
	v_lshl_add_u32 v73, v73, 2, s52
	v_lshl_add_u32 v76, v76, 2, s52
	v_lshl_add_u32 v77, v77, 2, s52
	v_lshl_add_u32 v80, v80, 2, s52
	v_lshl_add_u32 v81, v81, 2, s52
	v_lshl_add_u32 v82, v82, 2, s52
	v_med3_i32 v83, v87, 0, v184
	v_med3_i32 v84, v88, 0, v184
	v_med3_i32 v85, v89, 0, v184
	v_lshl_add_u32 v92, v92, 2, s52
	v_lshl_add_u32 v93, v93, 2, s52
	v_lshl_add_u32 v96, v96, 2, s52
	v_lshl_add_u32 v97, v97, 2, s52
	v_add_u32_e32 v159, -16, v66
	v_subrev_u32_e32 v164, 18, v66
	v_subrev_u32_e32 v165, 50, v66
	v_subrev_u32_e32 v180, 19, v66
	v_subrev_u32_e32 v190, 51, v66
	ds_read_b32 v68, v68
	ds_read_b32 v69, v69
	ds_read_b32 v72, v72
	ds_read_b32 v73, v73
	ds_read_b32 v76, v76
	ds_read_b32 v77, v77
	ds_read_b32 v80, v80
	ds_read_b32 v81, v81
	v_lshl_add_u32 v83, v83, 2, s52
	v_lshl_add_u32 v84, v84, 2, s52
	v_lshl_add_u32 v85, v85, 2, s52
	ds_read_b32 v154, v82
	ds_read_b32 v156, v83
	ds_read_b32 v157, v84
	ds_read_b32 v158, v85
	ds_read_b32 v92, v92
	ds_read_b32 v93, v93
	ds_read_b32 v96, v96
	ds_read_b32 v97, v97
	v_subrev_u32_e32 v160, 48, v66
	v_med3_i32 v82, v159, 0, v184
	v_subrev_u32_e32 v161, 17, v66
	v_subrev_u32_e32 v162, 49, v66
	v_med3_i32 v166, v164, 0, v184
	v_med3_i32 v167, v165, 0, v184
	v_med3_i32 v191, v180, 0, v184
	v_med3_i32 v192, v190, 0, v184
	v_lshl_add_u32 v82, v82, 2, s52
	v_med3_i32 v83, v160, 0, v184
	v_med3_i32 v84, v161, 0, v184
	v_med3_i32 v85, v162, 0, v184
	v_lshl_add_u32 v166, v166, 2, s52
	v_lshl_add_u32 v167, v167, 2, s52
	v_lshl_add_u32 v191, v191, 2, s52
	v_lshl_add_u32 v192, v192, 2, s52
	v_subrev_u32_e32 v197, 24, v66
	v_subrev_u32_e32 v201, 26, v66
	v_subrev_u32_e32 v202, 58, v66
	v_subrev_u32_e32 v205, 27, v66
	v_subrev_u32_e32 v206, 59, v66
	v_lshl_add_u32 v83, v83, 2, s52
	v_lshl_add_u32 v84, v84, 2, s52
	v_lshl_add_u32 v85, v85, 2, s52
	ds_read_b32 v193, v82
	ds_read_b32 v194, v83
	ds_read_b32 v195, v84
	ds_read_b32 v196, v85
	ds_read_b32 v166, v166
	ds_read_b32 v167, v167
	ds_read_b32 v191, v191
	ds_read_b32 v192, v192
	v_subrev_u32_e32 v198, 56, v66
	v_med3_i32 v82, v197, 0, v184
	v_subrev_u32_e32 v199, 25, v66
	v_subrev_u32_e32 v200, 57, v66
	v_med3_i32 v203, v201, 0, v184
	v_med3_i32 v204, v202, 0, v184
	v_med3_i32 v207, v205, 0, v184
	v_med3_i32 v208, v206, 0, v184
	v_lshl_add_u32 v82, v82, 2, s52
	v_med3_i32 v83, v198, 0, v184
	v_med3_i32 v84, v199, 0, v184
	v_med3_i32 v85, v200, 0, v184
	v_lshl_add_u32 v203, v203, 2, s52
	v_lshl_add_u32 v204, v204, 2, s52
	v_lshl_add_u32 v207, v207, 2, s52
	v_lshl_add_u32 v208, v208, 2, s52
	v_cmp_gt_u32_e32 vcc, s51, v66
	v_lshl_add_u32 v83, v83, 2, s52
	v_lshl_add_u32 v84, v84, 2, s52
	v_lshl_add_u32 v85, v85, 2, s52
	ds_read_b32 v209, v82
	ds_read_b32 v210, v83
	ds_read_b32 v211, v84
	ds_read_b32 v212, v85
	ds_read_b32 v203, v203
	ds_read_b32 v204, v204
	ds_read_b32 v207, v207
	ds_read_b32 v208, v208
	s_waitcnt lgkmcnt(0)
	v_cndmask_b32_e32 v82, v186, v68, vcc
	v_cmp_gt_u32_e32 vcc, s51, v67
	s_waitcnt lgkmcnt(0)
	s_nop 1
	v_cndmask_b32_e32 v66, v186, v69, vcc
	v_cmp_gt_u32_e32 vcc, s51, v70
	s_nop 1
	v_cndmask_b32_e32 v83, v186, v72, vcc
	v_cmp_gt_u32_e32 vcc, s51, v71
	s_nop 1
	v_cndmask_b32_e32 v67, v186, v73, vcc
	v_cmp_gt_u32_e32 vcc, s51, v74
	s_nop 1
	v_cndmask_b32_e32 v84, v186, v76, vcc
	v_cmp_gt_u32_e32 vcc, s51, v75
	s_nop 1
	v_cndmask_b32_e32 v68, v186, v77, vcc
	v_cmp_gt_u32_e32 vcc, s51, v78
	s_nop 1
	v_cndmask_b32_e32 v85, v186, v80, vcc
	v_cmp_gt_u32_e32 vcc, s51, v79
	s_nop 1
	v_cndmask_b32_e32 v69, v186, v81, vcc
	v_cmp_gt_u32_e32 vcc, s51, v86
	s_nop 1
	v_cndmask_b32_e32 v86, v186, v154, vcc
	v_cmp_gt_u32_e32 vcc, s51, v87
	s_nop 1
	v_cndmask_b32_e32 v70, v186, v156, vcc
	v_cmp_gt_u32_e32 vcc, s51, v88
	s_nop 1
	v_cndmask_b32_e32 v87, v186, v157, vcc
	v_cmp_gt_u32_e32 vcc, s51, v89
	s_nop 1
	v_cndmask_b32_e32 v71, v186, v158, vcc
	v_cmp_gt_u32_e32 vcc, s51, v90
	s_nop 1
	v_cndmask_b32_e32 v88, v186, v92, vcc
	v_cmp_gt_u32_e32 vcc, s51, v91
	s_nop 1
	v_cndmask_b32_e32 v72, v186, v93, vcc
	v_cmp_gt_u32_e32 vcc, s51, v94
	s_nop 1
	v_cndmask_b32_e32 v89, v186, v96, vcc
	v_cmp_gt_u32_e32 vcc, s51, v95
	s_nop 1
	v_cndmask_b32_e32 v73, v186, v97, vcc
	v_cmp_gt_u32_e32 vcc, s51, v159
	s_nop 1
	v_cndmask_b32_e32 v90, v186, v193, vcc
	v_cmp_gt_u32_e32 vcc, s51, v160
	s_nop 1
	v_cndmask_b32_e32 v74, v186, v194, vcc
	v_cmp_gt_u32_e32 vcc, s51, v161
	s_nop 1
	v_cndmask_b32_e32 v91, v186, v195, vcc
	v_cmp_gt_u32_e32 vcc, s51, v162
	s_nop 1
	v_cndmask_b32_e32 v75, v186, v196, vcc
	v_cmp_gt_u32_e32 vcc, s51, v164
	s_nop 1
	v_cndmask_b32_e32 v92, v186, v166, vcc
	v_cmp_gt_u32_e32 vcc, s51, v165
	s_nop 1
	v_cndmask_b32_e32 v76, v186, v167, vcc
	v_cmp_gt_u32_e32 vcc, s51, v180
	s_nop 1
	v_cndmask_b32_e32 v93, v186, v191, vcc
	v_cmp_gt_u32_e32 vcc, s51, v190
	s_nop 1
	v_cndmask_b32_e32 v77, v186, v192, vcc
	v_cmp_gt_u32_e32 vcc, s51, v197
	s_nop 1
	v_cndmask_b32_e32 v94, v186, v209, vcc
	v_cmp_gt_u32_e32 vcc, s51, v198
	s_nop 1
	v_cndmask_b32_e32 v78, v186, v210, vcc
	v_cmp_gt_u32_e32 vcc, s51, v199
	s_nop 1
	v_cndmask_b32_e32 v95, v186, v211, vcc
	v_cmp_gt_u32_e32 vcc, s51, v200
	s_nop 1
	v_cndmask_b32_e32 v79, v186, v212, vcc
	v_cmp_gt_u32_e32 vcc, s51, v201
	s_nop 1
	v_cndmask_b32_e32 v96, v186, v203, vcc
	v_cmp_gt_u32_e32 vcc, s51, v202
	s_nop 1
	v_cndmask_b32_e32 v80, v186, v204, vcc
	v_cmp_gt_u32_e32 vcc, s51, v205
	s_nop 1
	v_cndmask_b32_e32 v97, v186, v207, vcc
	v_cmp_gt_u32_e32 vcc, s51, v206
	s_nop 1
	v_cndmask_b32_e32 v81, v186, v208, vcc
	ds_read_b128 v[156:159], v153 offset:32768
	ds_read_b128 v[190:193], v153 offset:40960
	ds_read_b128 v[198:201], v145 offset:32768
	ds_read_b128 v[206:209], v145 offset:40960
	ds_read_b128 v[214:217], v135 offset:32768
	ds_read_b128 v[222:225], v135 offset:40960
	ds_read_b128 v[230:233], v134 offset:32768
	ds_read_b128 v[238:241], v134 offset:40960
	ds_read_b128 v[164:167], v153 offset:32896
	ds_read_b128 v[194:197], v153 offset:41088
	ds_read_b128 v[202:205], v145 offset:32896
	ds_read_b128 v[210:213], v145 offset:41088
	ds_read_b128 v[218:221], v135 offset:32896
	ds_read_b128 v[226:229], v135 offset:41088
	ds_read_b128 v[234:237], v134 offset:32896
	ds_read_b128 v[242:245], v134 offset:41088
	s_waitcnt lgkmcnt(8)
	v_mfma_f32_32x32x16_bf16 v[82:97], v[156:159], v[98:101], v[82:97]
	v_mfma_f32_32x32x16_bf16 v[66:81], v[190:193], v[98:101], v[66:81]
	v_mfma_f32_32x32x16_bf16 v[82:97], v[198:201], v[102:105], v[82:97]
	v_mfma_f32_32x32x16_bf16 v[66:81], v[206:209], v[102:105], v[66:81]
	v_mfma_f32_32x32x16_bf16 v[82:97], v[214:217], v[106:109], v[82:97]
	v_mfma_f32_32x32x16_bf16 v[66:81], v[222:225], v[106:109], v[66:81]
	v_mfma_f32_32x32x16_bf16 v[82:97], v[230:233], v[110:113], v[82:97]
	v_mfma_f32_32x32x16_bf16 v[66:81], v[238:241], v[110:113], v[66:81]
	s_waitcnt lgkmcnt(0)
	v_mfma_f32_32x32x16_bf16 v[82:97], v[164:167], v[114:117], v[82:97]
	v_mfma_f32_32x32x16_bf16 v[66:81], v[194:197], v[114:117], v[66:81]
	v_mfma_f32_32x32x16_bf16 v[82:97], v[202:205], v[118:121], v[82:97]
	v_mfma_f32_32x32x16_bf16 v[66:81], v[210:213], v[118:121], v[66:81]
	v_mfma_f32_32x32x16_bf16 v[82:97], v[218:221], v[122:125], v[82:97]
	v_mfma_f32_32x32x16_bf16 v[66:81], v[226:229], v[122:125], v[66:81]
	v_mfma_f32_32x32x16_bf16 v[82:97], v[234:237], v[126:129], v[82:97]
	v_mfma_f32_32x32x16_bf16 v[66:81], v[242:245], v[126:129], v[66:81]
